# attention: all waves run the deferred schedule; exp/sum/cvt interleaved with kk-major P.V MFMAs; row-sum order changed (f32)
# speedup vs baseline: 1.0231x; 1.0149x over previous
; #define ATT_STORE(buf) do { _Pragma("unroll") for (int i_ = 0; i_ < 2; ++i_) { const int c_ = tid + 512 * i_; const int key_ = c_ >> 4, part_ = c_ & 15, e_ = c_ >> 3, vp_ = c_ & 7; \
;         *(LAS u32x4*)(lds + (buf) * KBYTES + (key_ * KP + part_ * 8) * 2) = kreg[i_]; \
;         *(LAS u32x4*)(lds + 3 * KBYTES + (buf) * VBYTES + (e_ * VP + vp_ * 8) * 2) = vreg[i_]; } } while (0)
; DI void attn_unit(LAS unsigned char* lds, int tid, const bf16* __restrict__ P, const bf16* __restrict__ Vt, bf16* MG, int b, int h, int qrow0, int jt0, int jt1,
;                   float lam, float oscale, const float* subg) {
;     ...
;     const int lane = tid & 63, wave = tid >> 6, r32 = lane & 31, hi = lane >> 5;
;     const int qb = wave >> 1, m = wave & 1;
;     const int qrow = qrow0 + qb * 32 + r32;
;     bf16x8 qf[4];
; #pragma unroll
;     for (int ks = 0; ks < 4; ++ks) qf[ks] = *(const bf16x8*)(P + (size_t)qrow * NIN + h * 128 + m * 64 + ks * 16 + hi * 8);
;     f32x16 O[4];
; #pragma unroll
;     for (int es = 0; es < 4; ++es)
; #pragma unroll
;         for (int i = 0; i < 16; ++i) O[es][i] = 0.f;
;     float mrun = 0.f, lrun = 0.f;
;     u32x4 kreg[2], vreg[2];
;     const bf16* vbase = Vt + (size_t)(b * 4 + h) * 128 * NKEY;
;     ...
;     const bool halfB = wave >= 4;
;     ...
;     __syncthreads();
;     ATT_LOADG(jt0);
;     int buf = 0, pbuf = 2;
;     for (int j = jt0; j < jt1; ++j) {
;         ATT_STORE(buf);
;         __syncthreads();
;         if (j + 1 < jt1) ATT_LOADG(j + 1);
.LBB0_295:
	s_and_b32 s0, s14, 4
	s_or_b32 s2, s0, s8
	s_lshl_b32 s0, s14, 4
	s_lshl_b32 s3, s2, 10
	s_and_b32 s0, s0, 0xffffff80
	v_mov_b32_e32 v98, v152
	s_add_i32 s0, s3, s0
	v_readlane_b32 s16, v253, 6
	v_and_b32_e32 v101, 31, v98
	v_ashrrev_i32_e32 v168, 7, v98
	v_or_b32_e32 v0, s0, v101
	s_and_b32 s15, s14, 3
	v_ashrrev_i32_e32 v22, 6, v98
	v_lshl_add_u32 v156, v168, 5, v0
	v_mov_b64_e32 v[16:17], s[74:75]
	v_readlane_b32 s17, v253, 7
	v_and_b32_e32 v169, 1, v22
	v_mad_i64_i32 v[0:1], s[0:1], v156, s72, v[16:17]
	s_mov_b32 s5, s17
	s_lshl_b32 s4, s15, 8
	v_bfe_u32 v167, v98, 5, 1
	v_lshl_add_u64 v[0:1], v[0:1], 0, s[4:5]
	v_lshlrev_b32_e32 v146, 7, v169
	v_lshl_add_u64 v[0:1], v[0:1], 0, v[146:147]
	v_lshlrev_b32_e32 v154, 4, v167
	v_mov_b32_e32 v155, v147
	v_lshl_add_u64 v[0:1], v[0:1], 0, v[154:155]
	s_or_b32 s0, s2, s15
	global_load_dwordx4 v[112:115], v[0:1], off
	global_load_dwordx4 v[116:119], v[0:1], off offset:32
	global_load_dwordx4 v[120:123], v[0:1], off offset:64
	global_load_dwordx4 v[124:127], v[0:1], off offset:96
	s_mul_hi_i32 s1, s0, 0x110000
	s_mul_i32 s0, s0, 0x110000
	v_readlane_b32 s16, v253, 45
	v_lshlrev_b32_e32 v0, 3, v98
	v_readlane_b32 s17, v253, 46
	s_add_u32 s0, s16, s0
	v_and_b32_e32 v24, 56, v0
	v_add_u32_e32 v12, 0x200, v98
	s_addc_u32 s1, s17, s1
	v_and_b32_e32 v23, 0x78, v0
	v_lshlrev_b32_e32 v0, 1, v24
	v_mov_b32_e32 v1, v147
	v_ashrrev_i32_e32 v155, 4, v98
	v_ashrrev_i32_e32 v170, 4, v12
	v_lshl_add_u64 v[8:9], s[0:1], 0, v[0:1]
	v_add_u32_e32 v0, s3, v155
	v_add_u32_e32 v10, s3, v170
	v_mad_i64_i32 v[0:1], s[0:1], v0, s72, v[16:17]
	v_mad_i64_i32 v[10:11], s[0:1], v10, s72, v[16:17]
	v_lshl_add_u64 v[0:1], v[0:1], 0, s[4:5]
	v_lshlrev_b32_e32 v96, 1, v23
	v_mov_b32_e32 v97, v147
	v_lshl_add_u64 v[10:11], v[10:11], 0, s[4:5]
	v_lshl_add_u64 v[0:1], v[0:1], 0, v[96:97]
	v_ashrrev_i32_e32 v99, 3, v98
	s_movk_i32 s2, 0x2200
	v_lshl_add_u64 v[10:11], v[10:11], 0, v[96:97]
	v_ashrrev_i32_e32 v100, 3, v12
	s_barrier
	v_mad_i64_i32 v[18:19], s[0:1], v99, s2, v[8:9]
	global_load_dwordx4 v[0:3], v[0:1], off offset:1024
	s_nop 0
	global_load_dwordx4 v[4:7], v[18:19], off
	v_mad_i64_i32 v[20:21], s[0:1], v100, s2, v[8:9]
	global_load_dwordx4 v[8:11], v[10:11], off offset:1024
	s_nop 0
	global_load_dwordx4 v[12:15], v[20:21], off
	s_movk_i32 s0, 0x88
	s_movk_i32 s1, 0x48
	v_mul_lo_u32 v25, v155, s0
	v_mul_lo_u32 v26, v99, s1
	v_add_lshl_u32 v171, v25, v23, 1
	v_add_lshl_u32 v172, v26, v24, 1
	v_mul_lo_u32 v25, v170, s0
	v_mul_lo_u32 v26, v100, s1
	s_or_b32 s2, s3, 64
	v_add_u32_e32 v27, 0, v171
	v_add_lshl_u32 v173, v25, v23, 1
	v_add_lshl_u32 v174, v26, v24, 1
	v_add_u32_e32 v25, s2, v155
	v_add_u32_e32 v28, 0, v172
	v_add_u32_e32 v23, 0, v173
	v_add_u32_e32 v24, 0, v174
	s_mov_b32 s37, s5
	v_mul_u32_u24_e32 v176, 0x90, v101
	v_readlane_b32 s18, v253, 8
	v_readlane_b32 s19, v253, 9
	v_readlane_b32 s20, v253, 10
	v_readlane_b32 s21, v253, 11
	v_readlane_b32 s22, v253, 12
	v_readlane_b32 s23, v253, 13
	v_readlane_b32 s24, v253, 14
	v_readlane_b32 s25, v253, 15
	v_readlane_b32 s26, v253, 16
	s_waitcnt vmcnt(3)
	ds_write_b128 v27, v[0:3]
	s_waitcnt vmcnt(2)
	ds_write_b128 v28, v[4:7] offset:52224
	s_waitcnt vmcnt(1)
	ds_write_b128 v23, v[8:11]
	s_waitcnt vmcnt(0)
	ds_write_b128 v24, v[12:15] offset:52224
	v_mad_i64_i32 v[0:1], s[0:1], v25, s72, v[16:17]
	v_add_u32_e32 v2, s2, v170
	v_lshl_add_u64 v[0:1], v[0:1], 0, s[4:5]
	v_mad_i64_i32 v[2:3], s[0:1], v2, s72, v[16:17]
	v_lshl_add_u64 v[0:1], v[0:1], 0, v[96:97]
	v_lshl_add_u64 v[2:3], v[2:3], 0, s[4:5]
	s_waitcnt lgkmcnt(0)
	s_barrier
	v_lshl_add_u64 v[2:3], v[2:3], 0, v[96:97]
	global_load_dwordx4 v[132:135], v[0:1], off offset:1024
	global_load_dwordx4 v[136:139], v[2:3], off offset:1024
	global_load_dwordx4 v[128:131], v[18:19], off offset:128
	global_load_dwordx4 v[140:143], v[20:21], off offset:128
	v_mul_u32_u24_e32 v0, 0x110, v101
	v_add_u32_e32 v97, 0, v154
	s_mov_b64 s[0:1], exec
	s_mov_b64 s[4:5], 0
	v_add3_u32 v175, v97, v146, v0
	v_readlane_b32 s27, v253, 17
	v_readlane_b32 s28, v253, 18
	v_readlane_b32 s29, v253, 19
	v_readlane_b32 s30, v253, 20
	v_readlane_b32 s31, v253, 21
	s_and_saveexec_b64 s[2:3], s[4:5]
	s_xor_b64 s[2:3], exec, s[2:3]
	s_cbranch_execz .LBB0_297
	ds_read_b128 v[0:3], v175
	ds_read_b128 v[32:35], v175 offset:32
	s_movk_i32 s16, 0x90
	v_mad_u32_u24 v64, v101, s16, v97
	v_add_u32_e32 v78, 0xcc00, v64
	s_waitcnt lgkmcnt(1)
	v_mfma_f32_32x32x16_bf16 v[16:31], v[0:3], v[112:115], 0
	ds_read_b128 v[0:3], v175 offset:8704
	ds_read_b128 v[36:39], v175 offset:8736
	v_mul_u32_u24_e32 v176, 0x90, v101
	s_waitcnt lgkmcnt(1)
	v_mfma_f32_32x32x16_bf16 v[0:15], v[0:3], v[112:115], 0
	v_mfma_f32_32x32x16_bf16 v[16:31], v[32:35], v[116:119], v[16:31]
	s_waitcnt lgkmcnt(0)
	v_mfma_f32_32x32x16_bf16 v[0:15], v[36:39], v[116:119], v[0:15]
	ds_read_b128 v[32:35], v175 offset:64
	ds_read_b128 v[36:39], v175 offset:96
	s_waitcnt lgkmcnt(1)
	v_mfma_f32_32x32x16_bf16 v[16:31], v[32:35], v[120:123], v[16:31]
	ds_read_b128 v[32:35], v175 offset:8768
	ds_read_b128 v[40:43], v175 offset:8800
	s_waitcnt lgkmcnt(1)
	v_mfma_f32_32x32x16_bf16 v[0:15], v[32:35], v[120:123], v[0:15]
	v_and_b32_e32 v34, 64, v210
	v_xor_b32_e32 v33, 32, v210
	v_add_u32_e32 v34, 64, v34
	v_cmp_lt_i32_e32 vcc, v33, v34
	s_nop 1
	v_cndmask_b32_e32 v33, v210, v33, vcc
	v_mfma_f32_32x32x16_bf16 v[16:31], v[36:39], v[124:127], v[16:31]
	v_lshlrev_b32_e32 v33, 2, v33
	s_waitcnt lgkmcnt(0)
	v_mfma_f32_32x32x16_bf16 v[0:15], v[40:43], v[124:127], v[0:15]
	s_nop 15
	s_nop 7
	v_max3_f32 v32, v16, v0, v17
	s_nop 0
	v_max3_f32 v32, v32, v1, v18
	s_nop 0
	v_max3_f32 v32, v32, v2, v19
	s_nop 0
	v_max3_f32 v32, v32, v3, v20
	s_nop 0
	v_max3_f32 v32, v32, v4, v21
	s_nop 0
	v_max3_f32 v32, v32, v5, v22
	s_nop 0
	v_max3_f32 v32, v32, v6, v23
	s_nop 0
	v_max3_f32 v32, v32, v7, v24
	s_nop 0
	v_max3_f32 v32, v32, v8, v25
	s_nop 0
	v_max3_f32 v32, v32, v9, v26
	s_nop 0
	v_max3_f32 v32, v32, v10, v27
	s_nop 0
	v_max3_f32 v32, v32, v11, v28
	s_nop 0
	v_max3_f32 v32, v32, v12, v29
	s_nop 0
	v_max3_f32 v32, v32, v13, v30
	s_nop 0
	v_max3_f32 v32, v32, v14, v31
	s_nop 0
	v_max3_f32 v32, v32, v15, v32
	ds_bpermute_b32 v33, v33, v32
	s_waitcnt lgkmcnt(0)
	v_max3_f32 v65, v32, v33, v32
	s_nop 0
	v_sub_f32_e32 v0, v0, v65
	v_sub_f32_e32 v32, v4, v65
	v_sub_f32_e32 v4, v16, v65
	v_sub_f32_e32 v1, v1, v65
	v_sub_f32_e32 v33, v5, v65
	v_sub_f32_e32 v5, v17, v65
	v_exp_f32_e32 v42, v4
	v_exp_f32_e32 v43, v0
	v_sub_f32_e32 v2, v2, v65
	v_sub_f32_e32 v34, v6, v65
	v_sub_f32_e32 v6, v18, v65
	v_exp_f32_e32 v44, v5
	v_exp_f32_e32 v45, v1
	v_sub_f32_e32 v36, v8, v65
	v_exp_f32_e32 v4, v6
	v_exp_f32_e32 v8, v2
	v_add_f32_e32 v0, v43, v42
	v_sub_f32_e32 v37, v9, v65
	v_add_f32_e32 v5, 0, v0
	v_add_f32_e32 v9, v45, v44
	v_sub_f32_e32 v3, v3, v65
	v_sub_f32_e32 v38, v10, v65
	v_sub_f32_e32 v10, v19, v65
	v_pk_add_f32 v[0:1], v[8:9], v[4:5]
	v_sub_f32_e32 v35, v7, v65
	v_sub_f32_e32 v39, v11, v65
	v_sub_f32_e32 v11, v20, v65
	v_pk_add_f32 v[6:7], v[0:1], v[0:1] op_sel_hi:[0,1]
	v_exp_f32_e32 v5, v10
	v_exp_f32_e32 v9, v3
	v_exp_f32_e32 v6, v11
	v_exp_f32_e32 v10, v32
	v_sub_f32_e32 v16, v21, v65
	v_add_f32_e32 v11, v9, v5
	v_sub_f32_e32 v40, v12, v65
	v_pk_add_f32 v[0:1], v[10:11], v[6:7]
	v_sub_f32_e32 v41, v13, v65
	v_sub_f32_e32 v17, v22, v65
	v_pk_add_f32 v[12:13], v[0:1], v[0:1] op_sel_hi:[0,1]
	v_exp_f32_e32 v7, v16
	v_exp_f32_e32 v11, v33
	v_exp_f32_e32 v12, v17
	v_exp_f32_e32 v16, v34
	v_sub_f32_e32 v20, v23, v65
	v_add_f32_e32 v17, v11, v7
	v_sub_f32_e32 v2, v24, v65
	v_pk_add_f32 v[0:1], v[16:17], v[12:13]
	v_exp_f32_e32 v13, v20
	v_pk_add_f32 v[18:19], v[0:1], v[0:1] op_sel_hi:[0,1]
	v_exp_f32_e32 v17, v35
	v_exp_f32_e32 v18, v2
	v_exp_f32_e32 v20, v36
	v_sub_f32_e32 v3, v25, v65
	v_add_f32_e32 v21, v17, v13
	v_sub_f32_e32 v24, v26, v65
	v_pk_add_f32 v[0:1], v[20:21], v[18:19]
	v_exp_f32_e32 v19, v3
	v_pk_add_f32 v[22:23], v[0:1], v[0:1] op_sel_hi:[0,1]
	v_exp_f32_e32 v21, v37
	v_exp_f32_e32 v22, v24
	v_exp_f32_e32 v24, v38
	v_sub_f32_e32 v26, v27, v65
	v_add_f32_e32 v25, v21, v19
	v_sub_f32_e32 v2, v28, v65
	v_pk_add_f32 v[0:1], v[24:25], v[22:23]
	v_exp_f32_e32 v23, v26
	v_pk_add_f32 v[26:27], v[0:1], v[0:1] op_sel_hi:[0,1]
	v_exp_f32_e32 v26, v2
	ds_read_b128 v[0:3], v64 offset:52224
	v_exp_f32_e32 v25, v39
	v_exp_f32_e32 v28, v40
	v_cvt_pk_bf16_f32 v80, v42, v44
	v_cvt_pk_bf16_f32 v81, v4, v5
	v_cvt_pk_bf16_f32 v82, v6, v7
	v_cvt_pk_bf16_f32 v83, v12, v13
	ds_read_b128 v[4:7], v64 offset:52256
	v_sub_f32_e32 v32, v29, v65
	v_add_f32_e32 v29, v25, v23
	s_waitcnt lgkmcnt(1)
	v_mfma_f32_32x32x16_bf16 v[48:63], v[0:3], v[80:83], 0
	v_sub_f32_e32 v33, v30, v65
	v_sub_f32_e32 v34, v31, v65
	v_add_f32_e64 v30, v28, v26
	v_add_f32_e64 v31, v29, v27
	v_exp_f32_e32 v68, v32
	v_pk_add_f32 v[66:67], v[30:31], v[30:31] op_sel_hi:[0,1]
	v_exp_f32_e32 v66, v33
	v_exp_f32_e32 v12, v34
	v_cvt_pk_bf16_f32 v88, v18, v19
	v_cvt_pk_bf16_f32 v89, v22, v23
	v_cvt_pk_bf16_f32 v90, v26, v68
	v_cvt_pk_bf16_f32 v91, v66, v12
	ds_read_b128 v[0:3], v64 offset:52288
	v_cvt_pk_bf16_f32 v84, v43, v45
	s_waitcnt lgkmcnt(1)
	v_mfma_f32_32x32x16_bf16 v[48:63], v[4:7], v[88:91], v[48:63]
	v_cvt_pk_bf16_f32 v85, v8, v9
	v_cvt_pk_bf16_f32 v86, v10, v11
	v_cvt_pk_bf16_f32 v87, v16, v17
	ds_read_b128 v[4:7], v64 offset:52320
	v_sub_f32_e32 v13, v14, v65
	v_sub_f32_e32 v14, v15, v65
	v_exp_f32_e32 v9, v41
	s_waitcnt lgkmcnt(1)
	v_mfma_f32_32x32x16_bf16 v[48:63], v[0:3], v[84:87], v[48:63]
	v_exp_f32_e32 v8, v13
	v_exp_f32_e32 v10, v14
	v_cvt_pk_bf16_f32 v92, v20, v21
	v_cvt_pk_bf16_f32 v93, v24, v25
	v_cvt_pk_bf16_f32 v94, v28, v9
	v_cvt_pk_bf16_f32 v95, v8, v10
	v_add_f32_e32 v9, v9, v68
	s_waitcnt lgkmcnt(0)
	v_mfma_f32_32x32x16_bf16 v[48:63], v[4:7], v[92:95], v[48:63]
	ds_read_b128 v[0:3], v64 offset:56832
	ds_read_b128 v[4:7], v64 offset:56864
	s_waitcnt lgkmcnt(1)
	v_mfma_f32_32x32x16_bf16 v[32:47], v[0:3], v[80:83], 0
	s_waitcnt lgkmcnt(0)
	v_mfma_f32_32x32x16_bf16 v[32:47], v[4:7], v[88:91], v[32:47]
	ds_read_b128 v[0:3], v64 offset:56896
	ds_read_b128 v[4:7], v64 offset:56928
	s_waitcnt lgkmcnt(1)
	v_mfma_f32_32x32x16_bf16 v[32:47], v[0:3], v[84:87], v[32:47]
	s_waitcnt lgkmcnt(0)
	v_mfma_f32_32x32x16_bf16 v[32:47], v[4:7], v[92:95], v[32:47]
	ds_read_b128 v[0:3], v64 offset:61440
	ds_read_b128 v[4:7], v64 offset:61472
	s_waitcnt lgkmcnt(1)
	v_mfma_f32_32x32x16_bf16 v[16:31], v[0:3], v[80:83], 0
	s_waitcnt lgkmcnt(0)
	v_mfma_f32_32x32x16_bf16 v[16:31], v[4:7], v[88:91], v[16:31]
	ds_read_b128 v[0:3], v64 offset:61504
	ds_read_b128 v[4:7], v64 offset:61536
	ds_read_b128 v[68:71], v78 offset:13856
	v_add_f32_e32 v64, v10, v12
	ds_read_b128 v[74:77], v78 offset:13888
	ds_read_b128 v[102:105], v78 offset:13920
	s_waitcnt lgkmcnt(4)
	v_mfma_f32_32x32x16_bf16 v[16:31], v[0:3], v[84:87], v[16:31]
	ds_read_b128 v[0:3], v78 offset:13824
	s_waitcnt lgkmcnt(4)
	v_mfma_f32_32x32x16_bf16 v[16:31], v[4:7], v[92:95], v[16:31]
	v_add_f32_e64 v4, v8, v66
	v_add_f32_e64 v5, v9, v67
	v_add_f32_e64 v66, v4, v5
	v_add_f32_e64 v67, v5, v4
	v_mov_b32_e32 v67, v147
	v_pk_add_f32 v[158:159], v[64:65], v[66:67]
	s_waitcnt lgkmcnt(0)
	v_mfma_f32_32x32x16_bf16 v[0:15], v[0:3], v[80:83], 0
	v_xor_b32_e32 v64, 0x80000000, v159
	v_mov_b32_e32 v65, v64
	v_mov_b32_e32 v66, v64
	v_mov_b32_e32 v67, v64
	v_mov_b32_e32 v72, v64
	v_mov_b32_e32 v73, v64
	v_mov_b32_e32 v78, v64
	v_mfma_f32_32x32x16_bf16 v[0:15], v[68:71], v[88:91], v[0:15]
	v_mov_b32_e32 v68, v64
	v_mov_b32_e32 v69, v64
	v_mov_b32_e32 v70, v64
	v_mov_b32_e32 v71, v64
	v_mov_b32_e32 v79, v64
	v_mfma_f32_32x32x16_bf16 v[0:15], v[74:77], v[84:87], v[0:15]
	v_mov_b32_e32 v74, v64
	v_mov_b32_e32 v75, v64
	v_mov_b32_e32 v76, v64
	v_mov_b32_e32 v77, v64
	v_mfma_f32_32x32x16_bf16 v[0:15], v[102:105], v[92:95], v[0:15]

.LBB0_300:
	s_mov_b32 s19, s2
	s_mulk_i32 s2, 0x4400
	s_add_i32 s3, s2, 0
	s_lshl_b32 s20, s19, 10
	s_add_i32 s20, s3, s20
	v_add_u32_e32 v246, s3, v171
	v_add_u32_e32 v247, s20, v172
	s_waitcnt vmcnt(2)
	ds_write_b128 v246, v[132:135]
	s_waitcnt vmcnt(1)
	ds_write_b128 v247, v[128:131] offset:52224
	ds_write_b128 v246, v[136:139] offset:8704
	s_waitcnt vmcnt(0)
	ds_write_b128 v247, v[140:143] offset:61440
	v_add_u32_e32 v173, s2, v175
	s_mul_i32 s22, s21, 0x4800
	s_add_i32 s22, s22, 0xcc00
	v_add_u32_e32 v250, s22, v178
	ds_read_b128 v[188:191], v250
	ds_read_b128 v[192:195], v250 offset:4608
	ds_read_b128 v[196:199], v250 offset:9216
	ds_read_b128 v[200:203], v250 offset:13824
	ds_read_b128 v[204:207], v250 offset:32
	ds_read_b128 v[218:221], v250 offset:4640
	ds_read_b128 v[222:225], v250 offset:9248
	ds_read_b128 v[226:229], v250 offset:13856
	ds_read_b128 v[230:233], v250 offset:64
	ds_read_b128 v[234:237], v250 offset:4672
	ds_read_b128 v[238:241], v250 offset:9280
	s_waitcnt lgkmcnt(11)
	s_barrier
	s_cmpk_lg_i32 s17, 0x1080
	s_cbranch_scc0 .Latt1_noload
	s_cmp_lt_u32 s18, 63
	s_cselect_b32 s3, s16, s15
	s_add_i32 s3, s3, s17
	v_add_u32_e32 v246, s3, v155
	v_mad_i64_i32 v[246:247], s[22:23], v246, s72, v[160:161]
	v_add_u32_e32 v248, s3, v170
	global_load_dwordx4 v[128:131], v[162:163], off
	v_mad_i64_i32 v[248:249], s[22:23], v248, s72, v[160:161]
	global_load_dwordx4 v[132:135], v[246:247], off offset:1024
	global_load_dwordx4 v[136:139], v[248:249], off offset:1024
	global_load_dwordx4 v[140:143], v[164:165], off
.Latt1_noload:
	ds_read_b128 v[242:245], v250 offset:13888
	ds_read_b128 v[246:249], v250 offset:96
	ds_read_b128 v[180:183], v250 offset:4704
	ds_read_b128 v[184:187], v250 offset:9312
	s_cmp_eq_u32 s17, 0
	s_cbranch_scc1 .Latt1_first
	s_waitcnt lgkmcnt(14)
	v_mfma_f32_32x32x16_bf16 v[48:63], v[188:191], v[80:83], v[48:63]
	ds_read_b128 v[188:191], v250 offset:13920
	v_exp_f32_e32 v88, v88
	v_exp_f32_e32 v89, v89
	v_exp_f32_e32 v90, v90
	s_waitcnt lgkmcnt(14)
	v_mfma_f32_32x32x16_bf16 v[32:47], v[192:195], v[80:83], v[32:47]
	ds_read_b128 v[192:195], v173
	v_exp_f32_e32 v91, v91
	v_exp_f32_e32 v92, v92
	v_exp_f32_e32 v93, v93
	v_add_f32_e32 v145, v145, v88
	v_add_f32_e32 v146, v146, v89
	s_waitcnt lgkmcnt(14)
	v_mfma_f32_32x32x16_bf16 v[16:31], v[196:199], v[80:83], v[16:31]
	ds_read_b128 v[196:199], v173 offset:8704
	v_exp_f32_e32 v94, v94
	v_exp_f32_e32 v95, v95
	v_add_f32_e32 v150, v150, v90
	v_add_f32_e32 v151, v151, v91
	v_add_f32_e32 v145, v145, v92
	v_add_f32_e32 v146, v146, v93
	s_waitcnt lgkmcnt(14)
	v_mfma_f32_32x32x16_bf16 v[0:15], v[200:203], v[80:83], v[0:15]
	ds_read_b128 v[200:203], v173 offset:32
	v_cvt_pk_bf16_f32 v88, v88, v89
	v_cvt_pk_bf16_f32 v89, v90, v91
	v_cvt_pk_bf16_f32 v90, v92, v93
	v_cvt_pk_bf16_f32 v91, v94, v95
	v_add_f32_e32 v150, v150, v94
	v_add_f32_e32 v151, v151, v95
	s_waitcnt lgkmcnt(14)
	v_mfma_f32_32x32x16_bf16 v[48:63], v[204:207], v[88:91], v[48:63]
	ds_read_b128 v[204:207], v173 offset:8736
	v_exp_f32_e32 v96, v96
	v_exp_f32_e32 v97, v97
	v_exp_f32_e32 v98, v98
	s_waitcnt lgkmcnt(14)
	v_mfma_f32_32x32x16_bf16 v[32:47], v[218:221], v[88:91], v[32:47]
	ds_read_b128 v[218:221], v173 offset:64
	v_exp_f32_e32 v99, v99
	v_exp_f32_e32 v100, v100
	v_exp_f32_e32 v101, v101
	v_add_f32_e32 v145, v145, v96
	v_add_f32_e32 v146, v146, v97
	s_waitcnt lgkmcnt(14)
	v_mfma_f32_32x32x16_bf16 v[16:31], v[222:225], v[88:91], v[16:31]
	ds_read_b128 v[222:225], v173 offset:8768
	v_exp_f32_e32 v102, v102
	v_exp_f32_e32 v103, v103
	v_add_f32_e32 v150, v150, v98
	v_add_f32_e32 v151, v151, v99
	v_add_f32_e32 v145, v145, v100
	v_add_f32_e32 v146, v146, v101
	s_waitcnt lgkmcnt(14)
	v_mfma_f32_32x32x16_bf16 v[0:15], v[226:229], v[88:91], v[0:15]
	ds_read_b128 v[226:229], v173 offset:96
	v_cvt_pk_bf16_f32 v96, v96, v97
	v_cvt_pk_bf16_f32 v97, v98, v99
	v_cvt_pk_bf16_f32 v98, v100, v101
	v_cvt_pk_bf16_f32 v99, v102, v103
	v_add_f32_e32 v150, v150, v102
	v_add_f32_e32 v151, v151, v103
	s_waitcnt lgkmcnt(14)
	v_mfma_f32_32x32x16_bf16 v[48:63], v[230:233], v[96:99], v[48:63]
	ds_read_b128 v[230:233], v173 offset:8800
	v_exp_f32_e32 v104, v104
	v_exp_f32_e32 v105, v105
	v_exp_f32_e32 v106, v106
	s_waitcnt lgkmcnt(14)
	v_mfma_f32_32x32x16_bf16 v[32:47], v[234:237], v[96:99], v[32:47]
	v_exp_f32_e32 v107, v107
	v_exp_f32_e32 v108, v108
	v_exp_f32_e32 v109, v109
	v_add_f32_e32 v145, v145, v104
	v_add_f32_e32 v146, v146, v105
	s_waitcnt lgkmcnt(13)
	v_mfma_f32_32x32x16_bf16 v[16:31], v[238:241], v[96:99], v[16:31]
	v_exp_f32_e32 v110, v110
	v_exp_f32_e32 v111, v111
	v_add_f32_e32 v150, v150, v106
	v_add_f32_e32 v151, v151, v107
	v_add_f32_e32 v145, v145, v108
	v_add_f32_e32 v146, v146, v109
	s_waitcnt lgkmcnt(12)
	v_mfma_f32_32x32x16_bf16 v[0:15], v[242:245], v[96:99], v[0:15]
	v_cvt_pk_bf16_f32 v104, v104, v105
	v_cvt_pk_bf16_f32 v105, v106, v107
	v_cvt_pk_bf16_f32 v106, v108, v109
	v_cvt_pk_bf16_f32 v107, v110, v111
	v_add_f32_e32 v150, v150, v110
	v_add_f32_e32 v151, v151, v111
	s_waitcnt lgkmcnt(11)
	v_mfma_f32_32x32x16_bf16 v[48:63], v[246:249], v[104:107], v[48:63]
	v_add_f32_e32 v145, v145, v146
	s_waitcnt lgkmcnt(10)
	v_mfma_f32_32x32x16_bf16 v[32:47], v[180:183], v[104:107], v[32:47]
	v_add_f32_e32 v150, v150, v151
	s_waitcnt lgkmcnt(9)
	v_mfma_f32_32x32x16_bf16 v[16:31], v[184:187], v[104:107], v[16:31]
	v_add_f32_e32 v145, v145, v150
	s_waitcnt lgkmcnt(8)
	v_mfma_f32_32x32x16_bf16 v[0:15], v[188:191], v[104:107], v[0:15]
	v_add_f32_e32 v158, v158, v145
	s_branch .Latt1_qk
.Latt1_first:
	s_waitcnt lgkmcnt(14)
	v_mfma_f32_32x32x16_bf16 v[48:63], v[188:191], v[80:83], v[48:63]
	ds_read_b128 v[188:191], v250 offset:13920
	s_waitcnt lgkmcnt(14)
	v_mfma_f32_32x32x16_bf16 v[32:47], v[192:195], v[80:83], v[32:47]
	ds_read_b128 v[192:195], v173
	s_waitcnt lgkmcnt(14)
	v_mfma_f32_32x32x16_bf16 v[16:31], v[196:199], v[80:83], v[16:31]
	ds_read_b128 v[196:199], v173 offset:8704
	s_waitcnt lgkmcnt(14)
	v_mfma_f32_32x32x16_bf16 v[0:15], v[200:203], v[80:83], v[0:15]
	ds_read_b128 v[200:203], v173 offset:32
	s_waitcnt lgkmcnt(14)
	v_mfma_f32_32x32x16_bf16 v[48:63], v[204:207], v[88:91], v[48:63]
	ds_read_b128 v[204:207], v173 offset:8736
	s_waitcnt lgkmcnt(14)
	v_mfma_f32_32x32x16_bf16 v[32:47], v[218:221], v[88:91], v[32:47]
	ds_read_b128 v[218:221], v173 offset:64
	s_waitcnt lgkmcnt(14)
	v_mfma_f32_32x32x16_bf16 v[16:31], v[222:225], v[88:91], v[16:31]
	ds_read_b128 v[222:225], v173 offset:8768
	s_waitcnt lgkmcnt(14)
	v_mfma_f32_32x32x16_bf16 v[0:15], v[226:229], v[88:91], v[0:15]
	ds_read_b128 v[226:229], v173 offset:96
	s_waitcnt lgkmcnt(14)
	v_mfma_f32_32x32x16_bf16 v[48:63], v[230:233], v[84:87], v[48:63]
	ds_read_b128 v[230:233], v173 offset:8800
	s_waitcnt lgkmcnt(14)
	v_mfma_f32_32x32x16_bf16 v[32:47], v[234:237], v[84:87], v[32:47]
	s_waitcnt lgkmcnt(13)
	v_mfma_f32_32x32x16_bf16 v[16:31], v[238:241], v[84:87], v[16:31]
	s_waitcnt lgkmcnt(12)
	v_mfma_f32_32x32x16_bf16 v[0:15], v[242:245], v[84:87], v[0:15]
	s_waitcnt lgkmcnt(11)
	v_mfma_f32_32x32x16_bf16 v[48:63], v[246:249], v[92:95], v[48:63]
	s_waitcnt lgkmcnt(10)
	v_mfma_f32_32x32x16_bf16 v[32:47], v[180:183], v[92:95], v[32:47]
	s_waitcnt lgkmcnt(9)
	v_mfma_f32_32x32x16_bf16 v[16:31], v[184:187], v[92:95], v[16:31]
	s_waitcnt lgkmcnt(8)
	v_mfma_f32_32x32x16_bf16 v[0:15], v[188:191], v[92:95], v[0:15]
.Latt1_qk:
	s_waitcnt lgkmcnt(7)
	v_mfma_f32_32x32x16_bf16 v[80:95], v[192:195], v[112:115], v[64:79]
	s_waitcnt lgkmcnt(6)
	v_mfma_f32_32x32x16_bf16 v[96:111], v[196:199], v[112:115], v[64:79]
	s_waitcnt lgkmcnt(5)
	v_mfma_f32_32x32x16_bf16 v[80:95], v[200:203], v[116:119], v[80:95]
	s_waitcnt lgkmcnt(4)
	v_mfma_f32_32x32x16_bf16 v[96:111], v[204:207], v[116:119], v[96:111]
	s_waitcnt lgkmcnt(3)
	v_mfma_f32_32x32x16_bf16 v[80:95], v[218:221], v[120:123], v[80:95]
	s_waitcnt lgkmcnt(2)
	v_mfma_f32_32x32x16_bf16 v[96:111], v[222:225], v[120:123], v[96:111]
	s_waitcnt lgkmcnt(1)
	v_mfma_f32_32x32x16_bf16 v[80:95], v[226:229], v[124:127], v[80:95]
	s_waitcnt lgkmcnt(0)
	v_mfma_f32_32x32x16_bf16 v[96:111], v[230:233], v[124:127], v[96:111]
	s_nop 13
	v_max3_f32 v145, v80, v81, v82
	v_max3_f32 v146, v96, v97, v98
	v_max3_f32 v145, v145, v83, v84
	v_max3_f32 v146, v146, v99, v100
	v_max3_f32 v145, v145, v85, v86
	v_max3_f32 v146, v146, v101, v102
	v_max3_f32 v145, v145, v87, v88
	v_max3_f32 v146, v146, v103, v104
	v_max3_f32 v145, v145, v89, v90
	v_max3_f32 v146, v146, v105, v106
	v_max3_f32 v145, v145, v91, v92
	v_max3_f32 v146, v146, v107, v108
	v_max3_f32 v145, v145, v93, v94
	v_max3_f32 v146, v146, v109, v110
	v_max3_f32 v145, v145, v95, v111
	v_max_f32_e32 v145, v145, v146
	ds_bpermute_b32 v146, v209, v145
	s_waitcnt lgkmcnt(0)
	v_max_f32_e32 v146, v145, v146
	v_cmp_lt_f32_e32 vcc, 0x41000000, v146
	s_cbranch_vccz .Latt1_nors
	s_nop 0
	v_cndmask_b32_e32 v146, 0, v146, vcc
	v_exp_f32_e64 v150, -v146
	v_add_f32_e32 v159, v159, v146
	v_xor_b32_e32 v64, 0x80000000, v159
	v_mov_b32_e32 v65, v64
	v_mov_b32_e32 v66, v64
	v_mov_b32_e32 v67, v64
	v_mov_b32_e32 v68, v64
	v_mov_b32_e32 v69, v64
	v_mov_b32_e32 v70, v64
	v_mov_b32_e32 v71, v64
	v_mov_b32_e32 v72, v64
	v_mov_b32_e32 v73, v64
	v_mov_b32_e32 v74, v64
	v_mov_b32_e32 v75, v64
	v_mov_b32_e32 v76, v64
	v_mov_b32_e32 v77, v64
	v_mov_b32_e32 v78, v64
	v_mov_b32_e32 v79, v64
	v_mul_f32_e32 v158, v158, v150
	v_pk_mul_f32 v[14:15], v[14:15], v[150:151] op_sel_hi:[1,0]
	v_pk_mul_f32 v[12:13], v[12:13], v[150:151] op_sel_hi:[1,0]
	v_pk_mul_f32 v[10:11], v[10:11], v[150:151] op_sel_hi:[1,0]
	v_pk_mul_f32 v[8:9], v[8:9], v[150:151] op_sel_hi:[1,0]
	v_pk_mul_f32 v[6:7], v[6:7], v[150:151] op_sel_hi:[1,0]
	v_pk_mul_f32 v[4:5], v[4:5], v[150:151] op_sel_hi:[1,0]
	v_pk_mul_f32 v[2:3], v[2:3], v[150:151] op_sel_hi:[1,0]
	v_pk_mul_f32 v[0:1], v[0:1], v[150:151] op_sel_hi:[1,0]
	v_pk_mul_f32 v[30:31], v[30:31], v[150:151] op_sel_hi:[1,0]
	v_pk_mul_f32 v[28:29], v[28:29], v[150:151] op_sel_hi:[1,0]
	v_pk_mul_f32 v[26:27], v[26:27], v[150:151] op_sel_hi:[1,0]
	v_pk_mul_f32 v[24:25], v[24:25], v[150:151] op_sel_hi:[1,0]
	v_pk_mul_f32 v[22:23], v[22:23], v[150:151] op_sel_hi:[1,0]
	v_pk_mul_f32 v[20:21], v[20:21], v[150:151] op_sel_hi:[1,0]
	v_pk_mul_f32 v[18:19], v[18:19], v[150:151] op_sel_hi:[1,0]
	v_pk_mul_f32 v[16:17], v[16:17], v[150:151] op_sel_hi:[1,0]
	v_pk_mul_f32 v[46:47], v[46:47], v[150:151] op_sel_hi:[1,0]
	v_pk_mul_f32 v[44:45], v[44:45], v[150:151] op_sel_hi:[1,0]
	v_pk_mul_f32 v[42:43], v[42:43], v[150:151] op_sel_hi:[1,0]
	v_pk_mul_f32 v[40:41], v[40:41], v[150:151] op_sel_hi:[1,0]
	v_pk_mul_f32 v[38:39], v[38:39], v[150:151] op_sel_hi:[1,0]
	v_pk_mul_f32 v[36:37], v[36:37], v[150:151] op_sel_hi:[1,0]
	v_pk_mul_f32 v[34:35], v[34:35], v[150:151] op_sel_hi:[1,0]
	v_pk_mul_f32 v[32:33], v[32:33], v[150:151] op_sel_hi:[1,0]
	v_pk_mul_f32 v[62:63], v[62:63], v[150:151] op_sel_hi:[1,0]
	v_pk_mul_f32 v[60:61], v[60:61], v[150:151] op_sel_hi:[1,0]
	v_pk_mul_f32 v[58:59], v[58:59], v[150:151] op_sel_hi:[1,0]
	v_pk_mul_f32 v[56:57], v[56:57], v[150:151] op_sel_hi:[1,0]
	v_pk_mul_f32 v[54:55], v[54:55], v[150:151] op_sel_hi:[1,0]
	v_pk_mul_f32 v[52:53], v[52:53], v[150:151] op_sel_hi:[1,0]
	v_pk_mul_f32 v[50:51], v[50:51], v[150:151] op_sel_hi:[1,0]
; #define ATT_PV(bufv) do { \
;         const LAS bf16* Vb = (const LAS bf16*)(lds + 3 * KBYTES + (bufv) * VBYTES) + hi * 8; \
;         _Pragma("unroll") for (int es = 0; es < 4; ++es) _Pragma("unroll") for (int kk = 0; kk < 4; ++kk) { \
;             const bf16x8 a = *(const LAS bf16x8*)(Vb + (es * 32 + r32) * VP + kk * 16); O[es] = MFMA32(a, pf[kk], O[es]); } } while (0)
; DI void attn_unit(LAS unsigned char* lds, int tid, const bf16* __restrict__ P, const bf16* __restrict__ Vt, bf16* MG, int b, int h, int qrow0, int jt0, int jt1,
;                   float lam, float oscale, const float* subg) {
;     ...
;         pbuf = buf; buf = (buf == 2) ? 0 : buf + 1;
;     }
;     if (halfB) { ATT_PV(pbuf); }
	v_pk_mul_f32 v[48:49], v[48:49], v[150:151] op_sel_hi:[1,0]
	v_pk_add_f32 v[80:81], v[80:81], v[146:147] op_sel_hi:[1,0] neg_lo:[0,1] neg_hi:[0,1]
	v_pk_add_f32 v[96:97], v[96:97], v[146:147] op_sel_hi:[1,0] neg_lo:[0,1] neg_hi:[0,1]
	v_pk_add_f32 v[82:83], v[82:83], v[146:147] op_sel_hi:[1,0] neg_lo:[0,1] neg_hi:[0,1]
	v_pk_add_f32 v[98:99], v[98:99], v[146:147] op_sel_hi:[1,0] neg_lo:[0,1] neg_hi:[0,1]
	v_pk_add_f32 v[84:85], v[84:85], v[146:147] op_sel_hi:[1,0] neg_lo:[0,1] neg_hi:[0,1]
	v_pk_add_f32 v[100:101], v[100:101], v[146:147] op_sel_hi:[1,0] neg_lo:[0,1] neg_hi:[0,1]
	v_pk_add_f32 v[86:87], v[86:87], v[146:147] op_sel_hi:[1,0] neg_lo:[0,1] neg_hi:[0,1]
	v_pk_add_f32 v[102:103], v[102:103], v[146:147] op_sel_hi:[1,0] neg_lo:[0,1] neg_hi:[0,1]
	v_pk_add_f32 v[88:89], v[88:89], v[146:147] op_sel_hi:[1,0] neg_lo:[0,1] neg_hi:[0,1]
	v_pk_add_f32 v[104:105], v[104:105], v[146:147] op_sel_hi:[1,0] neg_lo:[0,1] neg_hi:[0,1]
	v_pk_add_f32 v[90:91], v[90:91], v[146:147] op_sel_hi:[1,0] neg_lo:[0,1] neg_hi:[0,1]
	v_pk_add_f32 v[106:107], v[106:107], v[146:147] op_sel_hi:[1,0] neg_lo:[0,1] neg_hi:[0,1]
	v_pk_add_f32 v[92:93], v[92:93], v[146:147] op_sel_hi:[1,0] neg_lo:[0,1] neg_hi:[0,1]
	v_pk_add_f32 v[108:109], v[108:109], v[146:147] op_sel_hi:[1,0] neg_lo:[0,1] neg_hi:[0,1]
	v_pk_add_f32 v[94:95], v[94:95], v[146:147] op_sel_hi:[1,0] neg_lo:[0,1] neg_hi:[0,1]
	v_pk_add_f32 v[110:111], v[110:111], v[146:147] op_sel_hi:[1,0] neg_lo:[0,1] neg_hi:[0,1]
.Latt1_nors:
	v_exp_f32_e32 v80, v80
	v_exp_f32_e32 v81, v81
	v_exp_f32_e32 v82, v82
	v_exp_f32_e32 v83, v83
	v_exp_f32_e32 v84, v84
	v_exp_f32_e32 v85, v85
	v_exp_f32_e32 v86, v86
	v_exp_f32_e32 v87, v87
	v_add_f32_e32 v145, v80, v81
	v_add_f32_e32 v146, v82, v83
	v_add_f32_e32 v150, v84, v85
	v_add_f32_e32 v151, v86, v87
	v_cvt_pk_bf16_f32 v80, v80, v81
	v_cvt_pk_bf16_f32 v81, v82, v83
	v_cvt_pk_bf16_f32 v82, v84, v85
	v_cvt_pk_bf16_f32 v83, v86, v87
	s_add_i32 s2, s19, 1
	s_cmp_lg_u32 s19, 2
	s_cselect_b32 s2, s2, 0
	s_add_i32 s17, s17, 64
	s_mov_b64 s[22:23], 0x80
	s_add_i32 s18, s18, 1
	v_lshl_add_u64 v[162:163], v[162:163], 0, s[22:23]
	s_cmpk_eq_i32 s17, 0x10c0
	v_lshl_add_u64 v[164:165], v[164:165], 0, s[22:23]
	s_cbranch_scc1 .LBB0_312
	s_mov_b32 s21, s19
	s_branch .LBB0_300
.LBB0_312:
	s_and_saveexec_b64 s[2:3], s[0:1]
	s_cbranch_execz .LBB0_314
	s_mul_i32 s22, s19, 0x4800
	s_add_i32 s22, s22, 0xcc00
	v_add_u32_e32 v250, s22, v178
	ds_read_b128 v[188:191], v250
	ds_read_b128 v[192:195], v250 offset:4608
	ds_read_b128 v[196:199], v250 offset:9216
	ds_read_b128 v[200:203], v250 offset:13824
	ds_read_b128 v[204:207], v250 offset:32
	ds_read_b128 v[218:221], v250 offset:4640
	ds_read_b128 v[222:225], v250 offset:9248
	ds_read_b128 v[226:229], v250 offset:13856
	ds_read_b128 v[230:233], v250 offset:64
	ds_read_b128 v[234:237], v250 offset:4672
	ds_read_b128 v[238:241], v250 offset:9280
	ds_read_b128 v[242:245], v250 offset:13888
	ds_read_b128 v[246:249], v250 offset:96
	ds_read_b128 v[180:183], v250 offset:4704
	ds_read_b128 v[184:187], v250 offset:9312
	s_waitcnt lgkmcnt(14)
	v_mfma_f32_32x32x16_bf16 v[48:63], v[188:191], v[80:83], v[48:63]
	ds_read_b128 v[188:191], v250 offset:13920
	v_exp_f32_e32 v88, v88
	v_exp_f32_e32 v89, v89
	v_exp_f32_e32 v90, v90
	s_waitcnt lgkmcnt(14)
	v_mfma_f32_32x32x16_bf16 v[32:47], v[192:195], v[80:83], v[32:47]
	v_exp_f32_e32 v91, v91
	v_exp_f32_e32 v92, v92
	v_exp_f32_e32 v93, v93
	v_add_f32_e32 v145, v145, v88
	v_add_f32_e32 v146, v146, v89
	s_waitcnt lgkmcnt(13)
	v_mfma_f32_32x32x16_bf16 v[16:31], v[196:199], v[80:83], v[16:31]
	v_exp_f32_e32 v94, v94
	v_exp_f32_e32 v95, v95
	v_add_f32_e32 v150, v150, v90
	v_add_f32_e32 v151, v151, v91
	v_add_f32_e32 v145, v145, v92
	v_add_f32_e32 v146, v146, v93
	s_waitcnt lgkmcnt(12)
	v_mfma_f32_32x32x16_bf16 v[0:15], v[200:203], v[80:83], v[0:15]
	v_cvt_pk_bf16_f32 v88, v88, v89
	v_cvt_pk_bf16_f32 v89, v90, v91
	v_cvt_pk_bf16_f32 v90, v92, v93
	v_cvt_pk_bf16_f32 v91, v94, v95
	v_add_f32_e32 v150, v150, v94
	v_add_f32_e32 v151, v151, v95
	s_waitcnt lgkmcnt(11)
	v_mfma_f32_32x32x16_bf16 v[48:63], v[204:207], v[88:91], v[48:63]
	v_exp_f32_e32 v96, v96
	v_exp_f32_e32 v97, v97
	v_exp_f32_e32 v98, v98
	s_waitcnt lgkmcnt(10)
	v_mfma_f32_32x32x16_bf16 v[32:47], v[218:221], v[88:91], v[32:47]
	v_exp_f32_e32 v99, v99
	v_exp_f32_e32 v100, v100
	v_exp_f32_e32 v101, v101
	v_add_f32_e32 v145, v145, v96
	v_add_f32_e32 v146, v146, v97
	s_waitcnt lgkmcnt(9)
	v_mfma_f32_32x32x16_bf16 v[16:31], v[222:225], v[88:91], v[16:31]
	v_exp_f32_e32 v102, v102
	v_exp_f32_e32 v103, v103
	v_add_f32_e32 v150, v150, v98
	v_add_f32_e32 v151, v151, v99
	v_add_f32_e32 v145, v145, v100
	v_add_f32_e32 v146, v146, v101
	s_waitcnt lgkmcnt(8)
	v_mfma_f32_32x32x16_bf16 v[0:15], v[226:229], v[88:91], v[0:15]
	v_cvt_pk_bf16_f32 v96, v96, v97
	v_cvt_pk_bf16_f32 v97, v98, v99
	v_cvt_pk_bf16_f32 v98, v100, v101
	v_cvt_pk_bf16_f32 v99, v102, v103
	v_add_f32_e32 v150, v150, v102
	v_add_f32_e32 v151, v151, v103
	s_waitcnt lgkmcnt(7)
	v_mfma_f32_32x32x16_bf16 v[48:63], v[230:233], v[96:99], v[48:63]
	v_exp_f32_e32 v104, v104
	v_exp_f32_e32 v105, v105
	v_exp_f32_e32 v106, v106
	s_waitcnt lgkmcnt(6)
	v_mfma_f32_32x32x16_bf16 v[32:47], v[234:237], v[96:99], v[32:47]
	v_exp_f32_e32 v107, v107
	v_exp_f32_e32 v108, v108
	v_exp_f32_e32 v109, v109
	v_add_f32_e32 v145, v145, v104
	v_add_f32_e32 v146, v146, v105
	s_waitcnt lgkmcnt(5)
	v_mfma_f32_32x32x16_bf16 v[16:31], v[238:241], v[96:99], v[16:31]
	v_exp_f32_e32 v110, v110
	v_exp_f32_e32 v111, v111
	v_add_f32_e32 v150, v150, v106
	v_add_f32_e32 v151, v151, v107
	v_add_f32_e32 v145, v145, v108
	v_add_f32_e32 v146, v146, v109
	s_waitcnt lgkmcnt(4)
	v_mfma_f32_32x32x16_bf16 v[0:15], v[242:245], v[96:99], v[0:15]
	v_cvt_pk_bf16_f32 v104, v104, v105
	v_cvt_pk_bf16_f32 v105, v106, v107
	v_cvt_pk_bf16_f32 v106, v108, v109
	v_cvt_pk_bf16_f32 v107, v110, v111
	v_add_f32_e32 v150, v150, v110
	v_add_f32_e32 v151, v151, v111
	s_waitcnt lgkmcnt(3)
	v_mfma_f32_32x32x16_bf16 v[48:63], v[246:249], v[104:107], v[48:63]
	v_add_f32_e32 v145, v145, v146
	s_waitcnt lgkmcnt(2)
	v_mfma_f32_32x32x16_bf16 v[32:47], v[180:183], v[104:107], v[32:47]
	v_add_f32_e32 v150, v150, v151
	s_waitcnt lgkmcnt(1)
	v_mfma_f32_32x32x16_bf16 v[16:31], v[184:187], v[104:107], v[16:31]
	v_add_f32_e32 v145, v145, v150
	s_waitcnt lgkmcnt(0)
	v_mfma_f32_32x32x16_bf16 v[0:15], v[188:191], v[104:107], v[0:15]
	v_add_f32_e32 v158, v158, v145
